# full-line stores extended to P4 y outputs (f32 pairs, two LDS scratch slots, counted vmcnt waits tightened)
# baseline (speedup 1.0000x reference)
; #define PG8_BAR __builtin_amdgcn_s_barrier()
; template <class Epi, class Sched, bool ALIGN_EPI>
; __device__ __forceinline__ unsigned long long gemm_phase(PG8_LAS unsigned char* lds, const Gemm g, const Sched& S, const Epi& E, const int probe_id) {
;     ...
;     const int tid = threadIdx.x, wid = __builtin_amdgcn_readfirstlane(tid >> 6), lane = tid & 63, wr = wid >> 2, wc = wid & 3, fr = lane & 15, fq = lane >> 4;
;     const int K = g.K, nt = K / BK;
;     unsigned voffA[2], voffB[2];
; #pragma unroll
;     for (int i = 0; i < 2; ++i) { int R, C; stage_rc(tid * 16 + i * 8192, R, C); const int Rb = Epi::PERM ? ((R & ~31) + perm32(R & 31)) : R;
;         voffA[i] = (unsigned)(R * g.lda + C) * 2u; voffB[i] = (unsigned)(Rb * g.ldb + C) * 2u; }
;     const size_t kstep = (size_t)(BK * 2);
;     const size_t hstepA = (size_t)HALF * g.lda * 2, hstepB = (size_t)HALF * g.ldb * 2;
;     const size_t tstepA = 2 * hstepA, tstepB = 2 * hstepB;
;     const unsigned ldsw = (unsigned)wid * 1024u;
;     const int aoff = lds_byte(wr * 64 + fr, fq * 8), boff = lds_byte(wc * 32 + fr, fq * 8);
;     ...
;     Unit cur, nxt; int ui = 0;
;     if (!S.next(0, cur)) return 0;
;     f32x4 acc[2][2][4][2];
; #pragma unroll
;     for (int a = 0; a < 2; ++a)
; #pragma unroll
;         for (int b = 0; b < 2; ++b)
; #pragma unroll
;             for (int m = 0; m < 4; ++m)
; #pragma unroll
;                 for (int n = 0; n < 2; ++n) acc[a][b][m][n] = (f32x4){0.f, 0.f, 0.f, 0.f};
;     bf16x8 At[4][2], B0[2][2], B1[2][2];
;     const char* cA = (const char*)g.A + (size_t)cur.pm * tstepA + (size_t)cur.kp * K * 2; const char* cB = (const char*)g.Bt + (size_t)cur.pn * tstepB + (size_t)cur.kp * K * 2;
;     PG8_STAGE(PG8_SB(0, 0), cB, voffB); PG8_STAGE(PG8_SB(0, 1), cB + hstepB, voffB); PG8_STAGE(PG8_SA(0, 0), cA, voffA); PG8_STAGE(PG8_SA(0, 1), cA + hstepA, voffA);
;     if (wr == 1) PG8_BAR;
; __global__ void __launch_bounds__(NWAVES * 64, 2) skel_fwd(Args args) {
;     ...
;     if (IN(4)) {
;         pg8::Gemm g{(const bf16*)(F.ws + WS_XN), (const bf16*)(F.ws + WS_WOUT), DM, DM, DM};
;         pg8::StaticOrder S; S.init(MP, DM, F.G, (int)blockIdx.x);
;         EpiOut E{F.in[0], F.in[1], F.out};
;         for (int rep = 0; rep < (PROBE_DUP == 6 ? 2 : 1); ++rep) pg8::gemm_phase<EpiOut, pg8::StaticOrder, false>(F.lds + RING_OFF, g, S, E, 0);
.LBB0_710:
	s_cmp_lt_i32 s94, 5
	s_cselect_b64 s[0:1], -1, 0
	s_cmp_gt_i32 s95, 4
	s_cselect_b64 s[2:3], -1, 0
	s_and_b64 s[0:1], s[0:1], s[2:3]
	s_andn2_b64 vcc, exec, s[0:1]
	s_cbranch_vccnz .LBB0_732
	s_add_u32 s4, s74, 0x2000000
	s_addc_u32 s5, s75, 0
	s_add_u32 s6, s74, 0x1600000
	s_addc_u32 s7, s75, 0
	s_add_u32 s8, s18, 0xf0000000
	s_addc_u32 s9, s19, -1
	s_cmpk_gt_i32 s89, 0x3ff
	v_readfirstlane_b32 s2, v0
	s_cbranch_scc1 .LBB0_727
	v_and_b32_e32 v244, 63, v0
	v_and_b32_e32 v245, 15, v244
	v_lshrrev_b32_e32 v246, 4, v244
	v_lshrrev_b32_e32 v247, 3, v244
	v_and_b32_e32 v248, 7, v244
	v_readfirstlane_b32 s98, v0
	s_nop 3
	s_lshr_b32 s98, s98, 6
	s_lshl_b32 s99, s98, 10
	s_add_i32 s99, s99, 0xc000
	v_and_b32_e32 v249, 7, v245
	v_lshrrev_b32_e32 v250, 3, v245
	v_lshlrev_b32_e32 v250, 13, v250
	v_lshl_add_u32 v250, v249, 7, v250
	v_add_u32_e32 v251, v246, v249
	v_and_b32_e32 v251, 7, v251
	v_lshl_add_u32 v224, v251, 4, v250
	v_add_u32_e32 v224, s99, v224
	v_add_u32_e32 v251, 4, v251
	v_and_b32_e32 v251, 7, v251
	v_lshl_add_u32 v225, v251, 4, v250
	v_add_u32_e32 v225, s99, v225
	v_add_u32_e32 v251, v248, v247
	v_and_b32_e32 v251, 7, v251
	v_lshlrev_b32_e32 v252, 7, v247
	v_lshl_add_u32 v226, v251, 4, v252
	v_add_u32_e32 v226, s99, v226
	s_mul_i32 s99, s98, 0x900
	s_add_i32 s99, s99, 0x21000
	v_mul_u32_u24_e32 v252, 0x90, v245
	v_lshl_add_u32 v227, v246, 4, v252
	v_add_u32_e32 v227, s99, v227
	v_mul_u32_u24_e32 v252, 0x90, v247
	v_lshl_add_u32 v228, v248, 4, v252
	v_add_u32_e32 v228, s99, v228
	v_sub_u32_e32 v252, v247, v245
	v_lshlrev_b32_e32 v252, 12, v252
	v_sub_u32_e32 v251, v248, v246
	v_lshl_add_u32 v242, v251, 4, v252
	v_ashrrev_i32_e32 v243, 31, v242
	s_mov_b32 s100, 0x8000
	s_mov_b32 s101, 0
	v_lshlrev_b32_e32 v1, 4, v0
	v_and_b32_e32 v2, 32, v0
	v_or_b32_e32 v13, 0x2000, v1
	v_bfe_u32 v12, v0, 2, 4
	v_bitop3_b32 v10, v1, v2, 48 bitop3:0x6c
	v_lshrrev_b32_e32 v1, 7, v13
	s_movk_i32 s0, 0x70
	s_ashr_i32 s40, s89, 31
	v_and_or_b32 v1, v1, s0, v12
	s_lshr_b32 s0, s40, 29
	s_add_i32 s0, s89, s0
	s_ashr_i32 s11, s0, 3
	s_and_b32 s0, s0, -8
	s_lshr_b32 s10, s2, 6
	s_sub_i32 s0, s89, s0
	s_lshr_b32 s1, s2, 8
	s_lshl_b32 s3, s10, 10
	s_lshl_b32 s13, s0, 7
	s_mul_i32 s12, s0, 0x81
	s_cmp_lt_i32 s0, 0
	s_cselect_b32 s0, s12, s13
	s_add_i32 s0, s0, s11
	s_ashr_i32 s11, s0, 31
	s_lshr_b32 s11, s11, 27
	s_add_i32 s11, s0, s11
	s_ashr_i32 s12, s11, 5
	s_and_b32 s11, s11, 0xffe0
	s_sub_i32 s11, s0, s11
	s_bfe_i32 s0, s11, 0x80000
	s_bfe_u32 s0, s0, 0x3000c
	s_add_i32 s13, s11, s0
	s_bfe_i32 s0, s13, 0x80000
	s_and_b32 s13, s13, 0xf8
	s_sub_i32 s11, s11, s13
	s_lshl_b32 s12, s12, 3
	s_sext_i32_i16 s0, s0
	s_sext_i32_i8 s11, s11
	s_lshr_b32 s0, s0, 3
	s_add_i32 s30, s12, s11
	s_ashr_i32 s31, s30, 31
	s_bfe_i64 s[14:15], s[0:1], 0x100000
	s_lshl_b64 s[12:13], s[30:31], 19
	s_lshl_b64 s[14:15], s[14:15], 19
	v_and_b32_e32 v11, 64, v0
	v_lshrrev_b32_e32 v3, 3, v0
	s_add_u32 s36, s6, s14
	v_or_b32_e32 v2, v10, v11
	v_and_or_b32 v3, v3, 48, v12
	s_addc_u32 s37, s7, s15
	s_add_i32 s31, s3, 0
	s_waitcnt vmcnt(0)
	v_lshl_or_b32 v130, v3, 11, v2
	s_add_i32 m0, s31, 0x10000
	v_lshl_or_b32 v132, v1, 11, v2
	global_load_lds_dwordx4 v130, s[36:37]
	s_add_i32 m0, s31, 0x12000
	s_add_u32 s14, s36, 0x40000
	global_load_lds_dwordx4 v132, s[36:37]
	s_addc_u32 s15, s37, 0
	s_add_i32 m0, s31, 0x14000
	v_mov_b32_e32 v131, 0
	global_load_lds_dwordx4 v130, s[14:15]
	s_add_i32 m0, s31, 0x16000
	s_add_u32 s34, s4, s12
	s_addc_u32 s35, s5, s13
	s_add_i32 s41, s31, 0x2000
	global_load_lds_dwordx4 v132, s[14:15]
	s_mov_b32 m0, s31
	s_add_u32 s12, s34, 0x40000
	global_load_lds_dwordx4 v130, s[34:35]
	s_mov_b32 m0, s41
	s_addc_u32 s13, s35, 0
	s_add_i32 s42, s31, 0x4000
	global_load_lds_dwordx4 v132, s[34:35]
	s_mov_b32 m0, s42
	s_add_i32 s43, s31, 0x6000
	global_load_lds_dwordx4 v130, s[12:13]
	s_mov_b32 m0, s43
	v_mov_b32_e32 v133, v131
	global_load_lds_dwordx4 v132, s[12:13]
	s_mov_b32 s44, 0
	v_lshl_add_u64 v[8:9], s[36:37], 0, v[130:131]
	v_lshl_add_u64 v[6:7], s[36:37], 0, v[132:133]
	v_lshl_add_u64 v[4:5], s[34:35], 0, v[130:131]
	s_cmp_lg_u32 s1, 1
	v_lshl_add_u64 v[2:3], s[34:35], 0, v[132:133]
	s_cbranch_scc1 .LBB0_714
	s_barrier

; #define PG8_STAGE(bufoff, gbase, voff) do { _Pragma("unroll") for (int _i = 0; _i < 2; ++_i) \
;         __builtin_amdgcn_global_load_lds((const unsigned*)((const char*)(gbase) + (voff)[_i]), (PG8_LAS unsigned*)(lds + (bufoff) + ldsw + _i * 8192), 16, 0, 0); } while (0)
; #define PG8_LDA(dst, b, h) do { _Pragma("unroll") for (int m = 0; m < 4; ++m) _Pragma("unroll") for (int k = 0; k < 2; ++k) dst[m][k] = *(const PG8_LAS bf16x8*)(lds + PG8_SA(b, h) + aoff + m * 2048 + k * 1024); } while (0)
; #define PG8_LDB(dst, b, h) do { _Pragma("unroll") for (int n = 0; n < 2; ++n) _Pragma("unroll") for (int k = 0; k < 2; ++k) dst[n][k] = *(const PG8_LAS bf16x8*)(lds + PG8_SB(b, h) + boff + n * 2048 + k * 1024); } while (0)
; #define PG8_MMA(ai, bj, At, Bt) do { __builtin_amdgcn_s_setprio(1); _Pragma("unroll") for (int m = 0; m < 4; ++m) _Pragma("unroll") for (int n = 0; n < 2; ++n) _Pragma("unroll") for (int k = 0; k < 2; ++k) \
;         acc[ai][bj][m][n] = __builtin_amdgcn_mfma_f32_16x16x32_bf16(Bt[n][k], At[m][k], acc[ai][bj][m][n], 0, 0, 0); __builtin_amdgcn_s_setprio(0); } while (0)
; #define PG8_WAIT_V(n) asm volatile("s_waitcnt vmcnt(" #n ")" ::: "memory")
; #define PG8_WAIT_L(n) asm volatile("s_waitcnt lgkmcnt(" #n ")" ::: "memory")
; #define PG8_BAR __builtin_amdgcn_s_barrier()
; #define PG8_SCHED __builtin_amdgcn_sched_barrier(0)
; template <class Epi, class Sched, bool ALIGN_EPI>
; __device__ __forceinline__ unsigned long long gemm_phase(PG8_LAS unsigned char* lds, const Gemm g, const Sched& S, const Epi& E, const int probe_id) {
;     ...
;         for (int t = 0; t < nt; t += 2) {
;             const bool last = (t == nt - 2);
;             const char* a1 = cA + (size_t)(t + 1) * kstep;
;             const char* a2 = last ? nA : cA + (size_t)(t + 2) * kstep; const char* b2 = last ? nB : cB + (size_t)(t + 2) * kstep;
;             const char* a3 = a2 + kstep; const char* b3 = b2 + kstep;
;             PG8_LDB(B0, 0, 0); PG8_LDB(B1, 0, 1); PG8_SCHED; PG8_LDA(At, 0, 0); PG8_STAGE(PG8_SA(1, 1), a1 + hstepA, voffA);
;             PG8_WAIT_V(8); PG8_WAIT_L(0); PG8_BAR; PG8_MMA(0, 0, At, B0); PG8_MMA(0, 1, At, B1); PG8_BAR; PG8_SCHED;
;             PG8_LDA(At, 0, 1); PG8_STAGE(PG8_SB(0, 0), b2, voffB); PG8_STAGE(PG8_SB(0, 1), b2 + hstepB, voffB); PG8_STAGE(PG8_SA(0, 0), a2, voffA);
.LBB0_722:
	ds_read_b128 v[150:153], v146
	ds_read_b128 v[154:157], v146 offset:1024
	ds_read_b128 v[158:161], v146 offset:2048
	ds_read_b128 v[162:165], v146 offset:3072
	ds_read_b128 v[166:169], v147
	ds_read_b128 v[170:173], v147 offset:1024
	ds_read_b128 v[174:177], v147 offset:2048
	ds_read_b128 v[178:181], v147 offset:3072
	s_add_u32 s36, s34, 0xfffc0080
	s_addc_u32 s37, s35, -1
	s_cmp_eq_u32 s55, 12
	s_cselect_b32 s39, s25, s37
	s_cselect_b32 s38, s51, s36
	s_cselect_b32 s37, s23, s54
	s_cselect_b32 s36, s52, s53
	v_lshl_add_u64 v[142:143], s[34:35], 0, v[134:135]
	s_add_i32 m0, s31, 0xc000
	ds_read_b128 v[182:185], v148
	ds_read_b128 v[186:189], v148 offset:1024
	ds_read_b128 v[190:193], v148 offset:2048
	ds_read_b128 v[194:197], v148 offset:3072
	ds_read_b128 v[198:201], v148 offset:4096
	ds_read_b128 v[202:205], v148 offset:5120
	ds_read_b128 v[206:209], v148 offset:6144
	ds_read_b128 v[210:213], v148 offset:7168
	global_load_lds_dwordx4 v[142:143], off
	v_lshl_add_u64 v[142:143], s[34:35], 0, v[136:137]
	s_add_i32 m0, s31, 0xe000
	s_nop 0
	global_load_lds_dwordx4 v[142:143], off
	s_waitcnt vmcnt(8)
	s_waitcnt lgkmcnt(0)
	s_barrier
	s_setprio 1
	s_waitcnt lgkmcnt(0)
	v_mfma_f32_16x16x32_bf16 v[126:129], v[150:153], v[182:185], v[126:129]
	v_mfma_f32_16x16x32_bf16 v[122:125], v[158:161], v[182:185], v[122:125]
	v_mfma_f32_16x16x32_bf16 v[118:121], v[150:153], v[190:193], v[118:121]
	v_mfma_f32_16x16x32_bf16 v[110:113], v[158:161], v[190:193], v[110:113]
	v_mfma_f32_16x16x32_bf16 v[98:101], v[150:153], v[198:201], v[98:101]
	v_mfma_f32_16x16x32_bf16 v[90:93], v[158:161], v[198:201], v[90:93]
	v_mfma_f32_16x16x32_bf16 v[86:89], v[150:153], v[206:209], v[86:89]
	v_mfma_f32_16x16x32_bf16 v[78:81], v[158:161], v[206:209], v[78:81]
	v_mfma_f32_16x16x32_bf16 v[126:129], v[154:157], v[186:189], v[126:129]
	v_mfma_f32_16x16x32_bf16 v[122:125], v[162:165], v[186:189], v[122:125]
	v_mfma_f32_16x16x32_bf16 v[118:121], v[154:157], v[194:197], v[118:121]
	v_mfma_f32_16x16x32_bf16 v[110:113], v[162:165], v[194:197], v[110:113]
	v_mfma_f32_16x16x32_bf16 v[98:101], v[154:157], v[202:205], v[98:101]
	v_mfma_f32_16x16x32_bf16 v[90:93], v[162:165], v[202:205], v[90:93]
	v_mfma_f32_16x16x32_bf16 v[86:89], v[154:157], v[210:213], v[86:89]
	v_mfma_f32_16x16x32_bf16 v[78:81], v[162:165], v[210:213], v[78:81]
	s_setprio 0
	s_setprio 1
	v_mfma_f32_16x16x32_bf16 v[114:117], v[166:169], v[182:185], v[114:117]
	v_mfma_f32_16x16x32_bf16 v[106:109], v[174:177], v[182:185], v[106:109]
	v_mfma_f32_16x16x32_bf16 v[102:105], v[166:169], v[190:193], v[102:105]
	v_mfma_f32_16x16x32_bf16 v[94:97], v[174:177], v[190:193], v[94:97]
	v_mfma_f32_16x16x32_bf16 v[82:85], v[166:169], v[198:201], v[82:85]
	v_mfma_f32_16x16x32_bf16 v[74:77], v[174:177], v[198:201], v[74:77]
	v_mfma_f32_16x16x32_bf16 v[70:73], v[166:169], v[206:209], v[70:73]
	v_mfma_f32_16x16x32_bf16 v[66:69], v[174:177], v[206:209], v[66:69]
	v_mfma_f32_16x16x32_bf16 v[114:117], v[170:173], v[186:189], v[114:117]
	v_mfma_f32_16x16x32_bf16 v[106:109], v[178:181], v[186:189], v[106:109]
	v_mfma_f32_16x16x32_bf16 v[102:105], v[170:173], v[194:197], v[102:105]
	v_mfma_f32_16x16x32_bf16 v[94:97], v[178:181], v[194:197], v[94:97]
	v_mfma_f32_16x16x32_bf16 v[82:85], v[170:173], v[202:205], v[82:85]
	v_mfma_f32_16x16x32_bf16 v[74:77], v[178:181], v[202:205], v[74:77]
	v_mfma_f32_16x16x32_bf16 v[70:73], v[170:173], v[210:213], v[70:73]
	v_mfma_f32_16x16x32_bf16 v[66:69], v[178:181], v[210:213], v[66:69]
	s_setprio 0
	s_barrier
	s_add_i32 s56, s48, s3
	v_lshl_add_u64 v[142:143], s[36:37], 0, v[130:131]
	s_mov_b32 m0, s56
	ds_read_b128 v[182:185], v148 offset:16384
	ds_read_b128 v[186:189], v148 offset:17408
	ds_read_b128 v[190:193], v148 offset:18432
	ds_read_b128 v[194:197], v148 offset:19456
	ds_read_b128 v[198:201], v148 offset:20480
	ds_read_b128 v[202:205], v148 offset:21504
	ds_read_b128 v[206:209], v148 offset:22528
	ds_read_b128 v[210:213], v148 offset:23552
	global_load_lds_dwordx4 v[142:143], off
	s_add_i32 m0, s56, 0x2000
	s_add_u32 s56, s36, 0x40000
	v_lshl_add_u64 v[214:215], s[36:37], 0, v[132:133]
	s_addc_u32 s57, s37, 0
	s_add_i32 s58, s49, s3
	global_load_lds_dwordx4 v[214:215], off
	v_lshl_add_u64 v[216:217], s[56:57], 0, v[130:131]
	s_mov_b32 m0, s58
	v_lshl_add_u64 v[218:219], s[38:39], 0, v[132:133]
	global_load_lds_dwordx4 v[216:217], off
	v_lshl_add_u64 v[216:217], s[56:57], 0, v[132:133]
	s_add_i32 m0, s58, 0x2000
	s_nop 0
	global_load_lds_dwordx4 v[216:217], off
	v_lshl_add_u64 v[216:217], s[38:39], 0, v[130:131]
	s_mov_b32 m0, s31
	s_nop 0
	global_load_lds_dwordx4 v[216:217], off
	s_mov_b32 m0, s41
	s_nop 0
	global_load_lds_dwordx4 v[218:219], off
	s_waitcnt vmcnt(8)
	s_waitcnt lgkmcnt(0)
	s_barrier
; #define PG8_STAGE(bufoff, gbase, voff) do { _Pragma("unroll") for (int _i = 0; _i < 2; ++_i) \
;         __builtin_amdgcn_global_load_lds((const unsigned*)((const char*)(gbase) + (voff)[_i]), (PG8_LAS unsigned*)(lds + (bufoff) + ldsw + _i * 8192), 16, 0, 0); } while (0)
; #define PG8_LDA(dst, b, h) do { _Pragma("unroll") for (int m = 0; m < 4; ++m) _Pragma("unroll") for (int k = 0; k < 2; ++k) dst[m][k] = *(const PG8_LAS bf16x8*)(lds + PG8_SA(b, h) + aoff + m * 2048 + k * 1024); } while (0)
; #define PG8_LDB(dst, b, h) do { _Pragma("unroll") for (int n = 0; n < 2; ++n) _Pragma("unroll") for (int k = 0; k < 2; ++k) dst[n][k] = *(const PG8_LAS bf16x8*)(lds + PG8_SB(b, h) + boff + n * 2048 + k * 1024); } while (0)
; #define PG8_MMA(ai, bj, At, Bt) do { __builtin_amdgcn_s_setprio(1); _Pragma("unroll") for (int m = 0; m < 4; ++m) _Pragma("unroll") for (int n = 0; n < 2; ++n) _Pragma("unroll") for (int k = 0; k < 2; ++k) \
;         acc[ai][bj][m][n] = __builtin_amdgcn_mfma_f32_16x16x32_bf16(Bt[n][k], At[m][k], acc[ai][bj][m][n], 0, 0, 0); __builtin_amdgcn_s_setprio(0); } while (0)
; #define PG8_WAIT_V(n) asm volatile("s_waitcnt vmcnt(" #n ")" ::: "memory")
; #define PG8_WAIT_L(n) asm volatile("s_waitcnt lgkmcnt(" #n ")" ::: "memory")
; #define PG8_BAR __builtin_amdgcn_s_barrier()
; #define PG8_SCHED __builtin_amdgcn_sched_barrier(0)
; template <class Epi, class Sched, bool ALIGN_EPI>
; __device__ __forceinline__ unsigned long long gemm_phase(PG8_LAS unsigned char* lds, const Gemm g, const Sched& S, const Epi& E, const int probe_id) {
;     ...
;             PG8_WAIT_V(8); PG8_WAIT_L(0); PG8_BAR; PG8_MMA(1, 0, At, B0); PG8_MMA(1, 1, At, B1); PG8_BAR; PG8_SCHED;
;             PG8_LDB(B0, 1, 0); PG8_LDB(B1, 1, 1); PG8_SCHED; PG8_LDA(At, 1, 0); PG8_STAGE(PG8_SA(0, 1), a2 + hstepA, voffA);
;             PG8_WAIT_V(8); PG8_WAIT_L(0); PG8_BAR; PG8_MMA(0, 0, At, B0); PG8_MMA(0, 1, At, B1); PG8_BAR; PG8_SCHED;
	s_setprio 1
	s_waitcnt lgkmcnt(0)
	v_mfma_f32_16x16x32_bf16 v[62:65], v[150:153], v[182:185], v[62:65]
	v_mfma_f32_16x16x32_bf16 v[58:61], v[158:161], v[182:185], v[58:61]
	v_mfma_f32_16x16x32_bf16 v[54:57], v[150:153], v[190:193], v[54:57]
	v_mfma_f32_16x16x32_bf16 v[46:49], v[158:161], v[190:193], v[46:49]
	v_mfma_f32_16x16x32_bf16 v[38:41], v[150:153], v[198:201], v[38:41]
	v_mfma_f32_16x16x32_bf16 v[26:29], v[158:161], v[198:201], v[26:29]
	v_mfma_f32_16x16x32_bf16 v[22:25], v[150:153], v[206:209], v[22:25]
	v_mfma_f32_16x16x32_bf16 v[14:17], v[158:161], v[206:209], v[14:17]
	v_mfma_f32_16x16x32_bf16 v[62:65], v[154:157], v[186:189], v[62:65]
	v_mfma_f32_16x16x32_bf16 v[58:61], v[162:165], v[186:189], v[58:61]
	v_mfma_f32_16x16x32_bf16 v[54:57], v[154:157], v[194:197], v[54:57]
	v_mfma_f32_16x16x32_bf16 v[46:49], v[162:165], v[194:197], v[46:49]
	v_mfma_f32_16x16x32_bf16 v[38:41], v[154:157], v[202:205], v[38:41]
	v_mfma_f32_16x16x32_bf16 v[26:29], v[162:165], v[202:205], v[26:29]
	v_mfma_f32_16x16x32_bf16 v[22:25], v[154:157], v[210:213], v[22:25]
	v_mfma_f32_16x16x32_bf16 v[14:17], v[162:165], v[210:213], v[14:17]
	s_setprio 0
	s_setprio 1
	v_mfma_f32_16x16x32_bf16 v[50:53], v[166:169], v[182:185], v[50:53]
	v_mfma_f32_16x16x32_bf16 v[42:45], v[174:177], v[182:185], v[42:45]
	v_mfma_f32_16x16x32_bf16 v[34:37], v[166:169], v[190:193], v[34:37]
	v_mfma_f32_16x16x32_bf16 v[30:33], v[174:177], v[190:193], v[30:33]
	v_mfma_f32_16x16x32_bf16 v[18:21], v[166:169], v[198:201], v[18:21]
	v_mfma_f32_16x16x32_bf16 v[10:13], v[174:177], v[198:201], v[10:13]
	v_mfma_f32_16x16x32_bf16 v[6:9], v[166:169], v[206:209], v[6:9]
	v_mfma_f32_16x16x32_bf16 v[2:5], v[174:177], v[206:209], v[2:5]
	v_mfma_f32_16x16x32_bf16 v[50:53], v[170:173], v[186:189], v[50:53]
	v_mfma_f32_16x16x32_bf16 v[42:45], v[178:181], v[186:189], v[42:45]
	v_mfma_f32_16x16x32_bf16 v[34:37], v[170:173], v[194:197], v[34:37]
	v_mfma_f32_16x16x32_bf16 v[30:33], v[178:181], v[194:197], v[30:33]
	v_mfma_f32_16x16x32_bf16 v[18:21], v[170:173], v[202:205], v[18:21]
	v_mfma_f32_16x16x32_bf16 v[10:13], v[178:181], v[202:205], v[10:13]
	v_mfma_f32_16x16x32_bf16 v[6:9], v[170:173], v[210:213], v[6:9]
	v_mfma_f32_16x16x32_bf16 v[2:5], v[178:181], v[210:213], v[2:5]
	s_setprio 0
	s_barrier
	s_add_i32 s56, 0, 0x18000
	v_add_u32_e32 v149, s56, v144
	s_add_i32 s57, 0, 0x1c000
	ds_read_b128 v[150:153], v149
	ds_read_b128 v[154:157], v149 offset:1024
	ds_read_b128 v[158:161], v149 offset:2048
	ds_read_b128 v[162:165], v149 offset:3072
	v_add_u32_e32 v149, s57, v144
	ds_read_b128 v[166:169], v149
	ds_read_b128 v[170:173], v149 offset:1024
	ds_read_b128 v[174:177], v149 offset:2048
	ds_read_b128 v[178:181], v149 offset:3072
	s_add_u32 s38, s38, 0x40000
	s_addc_u32 s39, s39, 0
	s_mov_b32 m0, s42
	v_lshl_add_u64 v[220:221], s[38:39], 0, v[130:131]
	ds_read_b128 v[182:185], v148 offset:32768
	ds_read_b128 v[186:189], v148 offset:33792
	ds_read_b128 v[190:193], v148 offset:34816
	ds_read_b128 v[194:197], v148 offset:35840
	ds_read_b128 v[198:201], v148 offset:36864
	ds_read_b128 v[202:205], v148 offset:37888
	ds_read_b128 v[206:209], v148 offset:38912
	ds_read_b128 v[210:213], v148 offset:39936
	global_load_lds_dwordx4 v[220:221], off
	v_lshl_add_u64 v[220:221], s[38:39], 0, v[132:133]
	s_mov_b32 m0, s43
	s_nop 0
	global_load_lds_dwordx4 v[220:221], off
	s_waitcnt vmcnt(8)
	s_waitcnt lgkmcnt(0)
	s_barrier
	s_setprio 1
	s_waitcnt lgkmcnt(0)
	v_mfma_f32_16x16x32_bf16 v[126:129], v[150:153], v[182:185], v[126:129]
	v_mfma_f32_16x16x32_bf16 v[122:125], v[158:161], v[182:185], v[122:125]
	v_mfma_f32_16x16x32_bf16 v[118:121], v[150:153], v[190:193], v[118:121]
	v_mfma_f32_16x16x32_bf16 v[110:113], v[158:161], v[190:193], v[110:113]
	v_mfma_f32_16x16x32_bf16 v[98:101], v[150:153], v[198:201], v[98:101]
	v_mfma_f32_16x16x32_bf16 v[90:93], v[158:161], v[198:201], v[90:93]
	v_mfma_f32_16x16x32_bf16 v[86:89], v[150:153], v[206:209], v[86:89]
	v_mfma_f32_16x16x32_bf16 v[78:81], v[158:161], v[206:209], v[78:81]
	v_mfma_f32_16x16x32_bf16 v[126:129], v[154:157], v[186:189], v[126:129]
	v_mfma_f32_16x16x32_bf16 v[122:125], v[162:165], v[186:189], v[122:125]
	v_mfma_f32_16x16x32_bf16 v[118:121], v[154:157], v[194:197], v[118:121]
	v_mfma_f32_16x16x32_bf16 v[110:113], v[162:165], v[194:197], v[110:113]
	v_mfma_f32_16x16x32_bf16 v[98:101], v[154:157], v[202:205], v[98:101]
	v_mfma_f32_16x16x32_bf16 v[90:93], v[162:165], v[202:205], v[90:93]
	v_mfma_f32_16x16x32_bf16 v[86:89], v[154:157], v[210:213], v[86:89]
	v_mfma_f32_16x16x32_bf16 v[78:81], v[162:165], v[210:213], v[78:81]
	s_setprio 0
	s_setprio 1
	v_mfma_f32_16x16x32_bf16 v[114:117], v[166:169], v[182:185], v[114:117]
	v_mfma_f32_16x16x32_bf16 v[106:109], v[174:177], v[182:185], v[106:109]
	v_mfma_f32_16x16x32_bf16 v[102:105], v[166:169], v[190:193], v[102:105]
	v_mfma_f32_16x16x32_bf16 v[94:97], v[174:177], v[190:193], v[94:97]
	v_mfma_f32_16x16x32_bf16 v[82:85], v[166:169], v[198:201], v[82:85]
	v_mfma_f32_16x16x32_bf16 v[74:77], v[174:177], v[198:201], v[74:77]
	v_mfma_f32_16x16x32_bf16 v[70:73], v[166:169], v[206:209], v[70:73]
	v_mfma_f32_16x16x32_bf16 v[66:69], v[174:177], v[206:209], v[66:69]
	v_mfma_f32_16x16x32_bf16 v[114:117], v[170:173], v[186:189], v[114:117]
	v_mfma_f32_16x16x32_bf16 v[106:109], v[178:181], v[186:189], v[106:109]
	v_mfma_f32_16x16x32_bf16 v[102:105], v[170:173], v[194:197], v[102:105]
	v_mfma_f32_16x16x32_bf16 v[94:97], v[178:181], v[194:197], v[94:97]
	v_mfma_f32_16x16x32_bf16 v[82:85], v[170:173], v[202:205], v[82:85]
	v_mfma_f32_16x16x32_bf16 v[74:77], v[178:181], v[202:205], v[74:77]
	v_mfma_f32_16x16x32_bf16 v[70:73], v[170:173], v[210:213], v[70:73]
	v_mfma_f32_16x16x32_bf16 v[66:69], v[178:181], v[210:213], v[66:69]
	s_setprio 0
	s_barrier
; #define PG8_STAGE(bufoff, gbase, voff) do { _Pragma("unroll") for (int _i = 0; _i < 2; ++_i) \
;         __builtin_amdgcn_global_load_lds((const unsigned*)((const char*)(gbase) + (voff)[_i]), (PG8_LAS unsigned*)(lds + (bufoff) + ldsw + _i * 8192), 16, 0, 0); } while (0)
; #define PG8_LDA(dst, b, h) do { _Pragma("unroll") for (int m = 0; m < 4; ++m) _Pragma("unroll") for (int k = 0; k < 2; ++k) dst[m][k] = *(const PG8_LAS bf16x8*)(lds + PG8_SA(b, h) + aoff + m * 2048 + k * 1024); } while (0)
; #define PG8_MMA(ai, bj, At, Bt) do { __builtin_amdgcn_s_setprio(1); _Pragma("unroll") for (int m = 0; m < 4; ++m) _Pragma("unroll") for (int n = 0; n < 2; ++n) _Pragma("unroll") for (int k = 0; k < 2; ++k) \
;         acc[ai][bj][m][n] = __builtin_amdgcn_mfma_f32_16x16x32_bf16(Bt[n][k], At[m][k], acc[ai][bj][m][n], 0, 0, 0); __builtin_amdgcn_s_setprio(0); } while (0)
; #define PG8_WAIT_V(n) asm volatile("s_waitcnt vmcnt(" #n ")" ::: "memory")
; #define PG8_WAIT_L(n) asm volatile("s_waitcnt lgkmcnt(" #n ")" ::: "memory")
; #define PG8_BAR __builtin_amdgcn_s_barrier()
; #define PG8_SCHED __builtin_amdgcn_sched_barrier(0)
; template <class Epi, class Sched, bool ALIGN_EPI>
; __device__ __forceinline__ unsigned long long gemm_phase(PG8_LAS unsigned char* lds, const Gemm g, const Sched& S, const Epi& E, const int probe_id) {
;     ...
;             PG8_LDA(At, 1, 1); PG8_STAGE(PG8_SB(1, 0), b3, voffB); PG8_STAGE(PG8_SB(1, 1), b3 + hstepB, voffB); PG8_STAGE(PG8_SA(1, 0), a3, voffA);
;             PG8_WAIT_V(8); PG8_WAIT_L(0); PG8_BAR; PG8_MMA(1, 0, At, B0); PG8_MMA(1, 1, At, B1); PG8_BAR; PG8_SCHED;
;         }
;     __device__ __forceinline__ bool operator()(pg8::f32x4 (&acc)[2][2][4][2], const pg8::Unit& u, int wr, int wc, int fr, int fq) const {
;         const int row0 = u.pm * 256 + wr * 64 + fr, col0 = u.pn * 256 + wc * 32 + 4 * fq;
;         const float* xb = (u.pm >= 256) ? xs - (size_t)MP * DM : xp;
;         f32x4 xv[2][2][2][2];
;     ...
;         LOADX(0, 0); __builtin_amdgcn_sched_barrier(0);
; #pragma unroll
;         for (int q = 0; q < 4; ++q) { const int ai = q >> 1, mh = q & 1, cb_ = q & 1;
;             if (q + 1 < 4) LOADX(cb_ ^ 1, q + 1);
	s_add_i32 s38, s56, s3
	v_lshl_add_u64 v[142:143], v[142:143], 0, s[10:11]
	s_mov_b32 m0, s38
	ds_read_b128 v[182:185], v148 offset:49152
	ds_read_b128 v[186:189], v148 offset:50176
	ds_read_b128 v[190:193], v148 offset:51200
	ds_read_b128 v[194:197], v148 offset:52224
	ds_read_b128 v[198:201], v148 offset:53248
	ds_read_b128 v[202:205], v148 offset:54272
	ds_read_b128 v[206:209], v148 offset:55296
	ds_read_b128 v[210:213], v148 offset:56320
	global_load_lds_dwordx4 v[142:143], off
	s_add_i32 m0, s38, 0x2000
	s_add_u32 s36, s36, 0x40080
	v_lshl_add_u64 v[142:143], v[214:215], 0, s[10:11]
	s_addc_u32 s37, s37, 0
	s_add_i32 s38, s57, s3
	global_load_lds_dwordx4 v[142:143], off
	v_lshl_add_u64 v[142:143], s[36:37], 0, v[130:131]
	s_mov_b32 m0, s38
	s_nop 0
	global_load_lds_dwordx4 v[142:143], off
	v_lshl_add_u64 v[142:143], s[36:37], 0, v[132:133]
	s_add_i32 m0, s38, 0x2000
	s_nop 0
	global_load_lds_dwordx4 v[142:143], off
	v_lshl_add_u64 v[142:143], v[216:217], 0, s[10:11]
	s_mov_b32 m0, s46
	s_nop 0
	global_load_lds_dwordx4 v[142:143], off
	v_lshl_add_u64 v[142:143], v[218:219], 0, s[10:11]
	s_mov_b32 m0, s47
	s_nop 0
	global_load_lds_dwordx4 v[142:143], off
	s_waitcnt vmcnt(8)
	s_waitcnt lgkmcnt(0)
	s_barrier
	s_setprio 1
	s_waitcnt lgkmcnt(0)
	v_mfma_f32_16x16x32_bf16 v[62:65], v[150:153], v[182:185], v[62:65]
	v_mfma_f32_16x16x32_bf16 v[58:61], v[158:161], v[182:185], v[58:61]
	v_mfma_f32_16x16x32_bf16 v[54:57], v[150:153], v[190:193], v[54:57]
	v_mfma_f32_16x16x32_bf16 v[46:49], v[158:161], v[190:193], v[46:49]
	v_mfma_f32_16x16x32_bf16 v[38:41], v[150:153], v[198:201], v[38:41]
	v_mfma_f32_16x16x32_bf16 v[26:29], v[158:161], v[198:201], v[26:29]
	v_mfma_f32_16x16x32_bf16 v[22:25], v[150:153], v[206:209], v[22:25]
	v_mfma_f32_16x16x32_bf16 v[14:17], v[158:161], v[206:209], v[14:17]
	v_mfma_f32_16x16x32_bf16 v[62:65], v[154:157], v[186:189], v[62:65]
	v_mfma_f32_16x16x32_bf16 v[58:61], v[162:165], v[186:189], v[58:61]
	v_mfma_f32_16x16x32_bf16 v[54:57], v[154:157], v[194:197], v[54:57]
	v_mfma_f32_16x16x32_bf16 v[46:49], v[162:165], v[194:197], v[46:49]
	v_mfma_f32_16x16x32_bf16 v[38:41], v[154:157], v[202:205], v[38:41]
	v_mfma_f32_16x16x32_bf16 v[26:29], v[162:165], v[202:205], v[26:29]
	v_mfma_f32_16x16x32_bf16 v[22:25], v[154:157], v[210:213], v[22:25]
	v_mfma_f32_16x16x32_bf16 v[14:17], v[162:165], v[210:213], v[14:17]
	s_setprio 0
	s_setprio 1
	v_mfma_f32_16x16x32_bf16 v[50:53], v[166:169], v[182:185], v[50:53]
	v_mfma_f32_16x16x32_bf16 v[42:45], v[174:177], v[182:185], v[42:45]
	v_mfma_f32_16x16x32_bf16 v[34:37], v[166:169], v[190:193], v[34:37]
	v_mfma_f32_16x16x32_bf16 v[30:33], v[174:177], v[190:193], v[30:33]
	v_mfma_f32_16x16x32_bf16 v[18:21], v[166:169], v[198:201], v[18:21]
	v_mfma_f32_16x16x32_bf16 v[10:13], v[174:177], v[198:201], v[10:13]
	v_mfma_f32_16x16x32_bf16 v[6:9], v[166:169], v[206:209], v[6:9]
	v_mfma_f32_16x16x32_bf16 v[2:5], v[174:177], v[206:209], v[2:5]
	v_mfma_f32_16x16x32_bf16 v[50:53], v[170:173], v[186:189], v[50:53]
	v_mfma_f32_16x16x32_bf16 v[42:45], v[178:181], v[186:189], v[42:45]
	v_mfma_f32_16x16x32_bf16 v[34:37], v[170:173], v[194:197], v[34:37]
	v_mfma_f32_16x16x32_bf16 v[30:33], v[178:181], v[194:197], v[30:33]
	v_mfma_f32_16x16x32_bf16 v[18:21], v[170:173], v[202:205], v[18:21]
	v_mfma_f32_16x16x32_bf16 v[10:13], v[178:181], v[202:205], v[10:13]
	v_mfma_f32_16x16x32_bf16 v[6:9], v[170:173], v[210:213], v[6:9]
	v_mfma_f32_16x16x32_bf16 v[2:5], v[178:181], v[210:213], v[2:5]
	s_setprio 0
	s_barrier
	s_add_i32 s55, s55, 2
	s_add_u32 s34, s34, 0x100
	s_addc_u32 s35, s35, 0
	s_add_u32 s53, s53, 0x100
	s_addc_u32 s54, s54, 0
	s_cmp_gt_u32 s55, 13
	s_cbranch_scc0 .LBB0_722
	v_lshl_add_u32 v198, s30, 8, v1
	v_lshl_or_b32 v142, s50, 8, v145
	s_cmpk_gt_i32 s30, 0xff
	v_ashrrev_i32_e32 v143, 31, v142
	v_or_b32_e32 v166, 16, v198
	s_cselect_b32 s35, s9, s17
	s_cselect_b32 s34, s8, s16
	v_lshlrev_b64 v[142:143], 2, v[142:143]
	v_ashrrev_i32_e32 v199, 31, v198
	v_ashrrev_i32_e32 v167, 31, v166
	v_lshl_add_u64 v[214:215], s[34:35], 0, v[142:143]
	v_lshlrev_b64 v[216:217], 12, v[198:199]
	v_lshlrev_b64 v[218:219], 12, v[166:167]
	v_lshl_add_u64 v[162:163], v[214:215], 0, v[216:217]
	v_lshl_add_u64 v[178:179], v[214:215], 0, v[218:219]
	global_load_dwordx4 v[150:153], v[162:163], off
	global_load_dwordx4 v[154:157], v[162:163], off offset:64
	global_load_dwordx4 v[158:161], v[162:163], off offset:512
	s_nop 0
	global_load_dwordx4 v[162:165], v[162:163], off offset:576
	s_nop 0
	global_load_dwordx4 v[166:169], v[178:179], off
	global_load_dwordx4 v[170:173], v[178:179], off offset:64
	global_load_dwordx4 v[174:177], v[178:179], off offset:512
	s_nop 0
	global_load_dwordx4 v[178:181], v[178:179], off offset:576
	v_or_b32_e32 v182, 32, v198
	v_or_b32_e32 v198, 48, v198
	v_ashrrev_i32_e32 v183, 31, v182
	v_ashrrev_i32_e32 v199, 31, v198
	v_lshlrev_b64 v[220:221], 12, v[182:183]
	v_lshlrev_b64 v[222:223], 12, v[198:199]
	v_lshl_add_u64 v[194:195], v[214:215], 0, v[220:221]
	v_lshl_add_u64 v[210:211], v[214:215], 0, v[222:223]
	global_load_dwordx4 v[182:185], v[194:195], off
	global_load_dwordx4 v[186:189], v[194:195], off offset:64
	global_load_dwordx4 v[190:193], v[194:195], off offset:512
	s_nop 0
	global_load_dwordx4 v[194:197], v[194:195], off offset:576
	s_nop 0
	global_load_dwordx4 v[198:201], v[210:211], off
	global_load_dwordx4 v[202:205], v[210:211], off offset:64
	global_load_dwordx4 v[206:209], v[210:211], off offset:512
	s_nop 0
	global_load_dwordx4 v[210:213], v[210:211], off offset:576
	s_waitcnt vmcnt(0)
; #define GAS __attribute__((address_space(1)))
; #define LOADX(buf, q) do { _Pragma("unroll") for (int m = 0; m < 2; ++m) _Pragma("unroll") for (int bj = 0; bj < 2; ++bj) _Pragma("unroll") for (int n = 0; n < 2; ++n) \
;             xv[buf][m][bj][n] = *(const GAS f32x4*)(xb + (size_t)(row0 + ((q) >> 1) * 128 + (2 * ((q) & 1) + m) * 16) * DM + col0 + bj * 128 + n * 16); } while (0)
;     __device__ __forceinline__ bool operator()(pg8::f32x4 (&acc)[2][2][4][2], const pg8::Unit& u, int wr, int wc, int fr, int fq) const {
;     ...
;         for (int q = 0; q < 4; ++q) { const int ai = q >> 1, mh = q & 1, cb_ = q & 1;
;             if (q + 1 < 4) LOADX(cb_ ^ 1, q + 1);
;             __builtin_amdgcn_sched_barrier(0);
; #pragma unroll
;             for (int m = 0; m < 2; ++m)
; #pragma unroll
;                 for (int bj = 0; bj < 2; ++bj)
; #pragma unroll
;                     for (int n = 0; n < 2; ++n) { const pg8::f32x4 a = acc[ai][bj][2 * mh + m][n]; const f32x4 x = xv[cb_][m][bj][n];
;                         *(GAS f32x4*)(out + (size_t)(row0 + ai * 128 + (2 * mh + m) * 16) * DM + col0 + bj * 128 + n * 16) = (f32x4){x.x + a.x, x.y + a.y, x.z + a.z, x.w + a.w}; }
;             __builtin_amdgcn_sched_barrier(0);
;         }
	v_pk_add_f32 v[126:127], v[126:127], v[150:151]
	v_lshl_add_u64 v[150:151], s[72:73], 0, v[216:217]
	v_lshl_add_u64 v[150:151], v[150:151], 0, v[142:143]
	v_pk_add_f32 v[116:117], v[116:117], v[160:161]
	v_pk_add_f32 v[114:115], v[114:115], v[158:159]
	ds_write_b128 v224, v[114:117]
	v_pk_add_f32 v[108:109], v[108:109], v[164:165]
	v_pk_add_f32 v[106:107], v[106:107], v[162:163]
	v_lshl_add_u64 v[114:115], s[72:73], 0, v[218:219]
	ds_write_b128 v225, v[106:109]
	ds_read_b128 v[230:233], v226
	ds_read_b128 v[234:237], v226 offset:8192
	v_lshl_add_u64 v[238:239], v[150:151], 0, v[242:243]
	v_lshl_add_u64 v[240:241], v[238:239], 0, s[100:101]
	s_waitcnt lgkmcnt(0)
	global_store_dwordx4 v[238:239], v[230:233], off offset:512
	global_store_dwordx4 v[240:241], v[234:237], off offset:512
	v_lshl_add_u64 v[114:115], v[114:115], 0, v[142:143]
	v_pk_add_f32 v[128:129], v[128:129], v[152:153]
	v_pk_add_f32 v[108:109], v[120:121], v[168:169]
	v_pk_add_f32 v[106:107], v[118:119], v[166:167]
	v_pk_add_f32 v[124:125], v[124:125], v[156:157]
	v_pk_add_f32 v[122:123], v[122:123], v[154:155]
	ds_write_b128 v224, v[106:109]
	v_pk_add_f32 v[104:105], v[104:105], v[176:177]
	v_pk_add_f32 v[102:103], v[102:103], v[174:175]
	v_pk_add_f32 v[108:109], v[112:113], v[172:173]
	v_pk_add_f32 v[106:107], v[110:111], v[170:171]
	v_pk_add_f32 v[96:97], v[96:97], v[180:181]
	v_pk_add_f32 v[94:95], v[94:95], v[178:179]
	ds_write_b128 v227, v[126:129]
	ds_write_b128 v227, v[122:125] offset:64
	ds_read_b128 v[230:233], v228
	ds_read_b128 v[234:237], v228 offset:1152
	v_lshl_add_u64 v[238:239], v[150:151], 0, v[242:243]
	v_lshl_add_u64 v[240:241], v[238:239], 0, s[100:101]
	s_waitcnt lgkmcnt(0)
	global_store_dwordx4 v[238:239], v[230:233], off
	global_store_dwordx4 v[240:241], v[234:237], off
	ds_write_b128 v225, v[106:109]
	ds_read_b128 v[230:233], v226
	ds_read_b128 v[234:237], v226 offset:8192
	v_lshl_add_u64 v[238:239], v[114:115], 0, v[242:243]
	v_lshl_add_u64 v[240:241], v[238:239], 0, s[100:101]
	s_waitcnt lgkmcnt(0)
	global_store_dwordx4 v[238:239], v[230:233], off
	global_store_dwordx4 v[240:241], v[234:237], off
	ds_write_b128 v224, v[102:105]
	ds_write_b128 v225, v[94:97]
	ds_read_b128 v[230:233], v226
	ds_read_b128 v[234:237], v226 offset:8192
	v_lshl_add_u64 v[238:239], v[114:115], 0, v[242:243]
	v_lshl_add_u64 v[240:241], v[238:239], 0, s[100:101]
	s_waitcnt lgkmcnt(0)
	global_store_dwordx4 v[238:239], v[230:233], off offset:512
	global_store_dwordx4 v[240:241], v[234:237], off offset:512
	v_lshl_add_u64 v[150:151], v[216:217], 0, s[12:13]
	v_lshl_add_u64 v[152:153], v[216:217], 0, s[14:15]
	v_lshl_add_u64 v[110:111], v[214:215], 0, v[150:151]
	v_lshl_add_u64 v[126:127], v[214:215], 0, v[152:153]
	global_load_dwordx4 v[94:97], v[110:111], off
	global_load_dwordx4 v[102:105], v[110:111], off offset:64
	global_load_dwordx4 v[106:109], v[110:111], off offset:512
	s_nop 0
	global_load_dwordx4 v[110:113], v[110:111], off offset:576
	s_nop 0
	global_load_dwordx4 v[114:117], v[126:127], off
	global_load_dwordx4 v[118:121], v[126:127], off offset:64
	global_load_dwordx4 v[122:125], v[126:127], off offset:512
	s_nop 0
	global_load_dwordx4 v[126:129], v[126:127], off offset:576
	v_lshl_add_u64 v[154:155], s[72:73], 0, v[220:221]
	v_lshl_add_u64 v[154:155], v[154:155], 0, v[142:143]
	v_pk_add_f32 v[84:85], v[84:85], v[192:193]
	v_pk_add_f32 v[82:83], v[82:83], v[190:191]
	ds_write_b128 v224, v[82:85]
	v_pk_add_f32 v[76:77], v[76:77], v[196:197]
	v_pk_add_f32 v[74:75], v[74:75], v[194:195]
	v_lshl_add_u64 v[82:83], s[72:73], 0, v[222:223]
	ds_write_b128 v225, v[74:77]
	ds_read_b128 v[230:233], v226
	ds_read_b128 v[234:237], v226 offset:8192
	v_lshl_add_u64 v[238:239], v[154:155], 0, v[242:243]
	v_lshl_add_u64 v[240:241], v[238:239], 0, s[100:101]
	s_waitcnt lgkmcnt(0)
	global_store_dwordx4 v[238:239], v[230:233], off offset:512
	global_store_dwordx4 v[240:241], v[234:237], off offset:512
	v_lshl_add_u64 v[82:83], v[82:83], 0, v[142:143]
	v_pk_add_f32 v[100:101], v[100:101], v[184:185]
	v_pk_add_f32 v[76:77], v[88:89], v[200:201]
	v_pk_add_f32 v[74:75], v[86:87], v[198:199]
	v_pk_add_f32 v[98:99], v[98:99], v[182:183]
	v_pk_add_f32 v[92:93], v[92:93], v[188:189]
	v_pk_add_f32 v[90:91], v[90:91], v[186:187]
	ds_write_b128 v224, v[74:77]
	v_pk_add_f32 v[72:73], v[72:73], v[208:209]
	v_pk_add_f32 v[70:71], v[70:71], v[206:207]
	v_pk_add_f32 v[76:77], v[80:81], v[204:205]
	v_pk_add_f32 v[74:75], v[78:79], v[202:203]
	v_pk_add_f32 v[68:69], v[68:69], v[212:213]
	v_pk_add_f32 v[66:67], v[66:67], v[210:211]
	ds_write_b128 v227, v[98:101]
	ds_write_b128 v227, v[90:93] offset:64
	ds_read_b128 v[230:233], v228
	ds_read_b128 v[234:237], v228 offset:1152
	v_lshl_add_u64 v[238:239], v[154:155], 0, v[242:243]
	v_lshl_add_u64 v[240:241], v[238:239], 0, s[100:101]
	s_waitcnt lgkmcnt(0)
	global_store_dwordx4 v[238:239], v[230:233], off
	global_store_dwordx4 v[240:241], v[234:237], off
	ds_write_b128 v225, v[74:77]
	ds_read_b128 v[230:233], v226
	ds_read_b128 v[234:237], v226 offset:8192
	v_lshl_add_u64 v[238:239], v[82:83], 0, v[242:243]
	v_lshl_add_u64 v[240:241], v[238:239], 0, s[100:101]
	s_waitcnt lgkmcnt(0)
	global_store_dwordx4 v[238:239], v[230:233], off
	global_store_dwordx4 v[240:241], v[234:237], off
	ds_write_b128 v224, v[70:73]
	ds_write_b128 v225, v[66:69]
	ds_read_b128 v[230:233], v226
	ds_read_b128 v[234:237], v226 offset:8192
	v_lshl_add_u64 v[238:239], v[82:83], 0, v[242:243]
	v_lshl_add_u64 v[240:241], v[238:239], 0, s[100:101]
	s_waitcnt lgkmcnt(0)
; #define PG8_WAIT_V(n) asm volatile("s_waitcnt vmcnt(" #n ")" ::: "memory")
; #define PG8_BAR __builtin_amdgcn_s_barrier()
; #define GAS __attribute__((address_space(1)))
; #define LOADX(buf, q) do { _Pragma("unroll") for (int m = 0; m < 2; ++m) _Pragma("unroll") for (int bj = 0; bj < 2; ++bj) _Pragma("unroll") for (int n = 0; n < 2; ++n) \
;             xv[buf][m][bj][n] = *(const GAS f32x4*)(xb + (size_t)(row0 + ((q) >> 1) * 128 + (2 * ((q) & 1) + m) * 16) * DM + col0 + bj * 128 + n * 16); } while (0)
; template <class Epi, class Sched, bool ALIGN_EPI>
; __device__ __forceinline__ unsigned long long gemm_phase(PG8_LAS unsigned char* lds, const Gemm g, const Sched& S, const Epi& E, const int probe_id) {
;     ...
;         if (!has_next) break;
;         if (!keep) {
; #pragma unroll
;         for (int a = 0; a < 2; ++a)
; #pragma unroll
;             for (int b = 0; b < 2; ++b)
; #pragma unroll
;                 for (int m = 0; m < 4; ++m)
; #pragma unroll
;                     for (int n = 0; n < 2; ++n) acc[a][b][m][n] = (f32x4){0.f, 0.f, 0.f, 0.f};
;         }
;         cur = nxt; cA = nA; cB = nB; ++ui;
;         if constexpr (ALIGN_EPI) { if (wr == 1) PG8_BAR; }
;     }
;     PG8_WAIT_V(0);
;     if constexpr (!ALIGN_EPI) { if (wr == 0) PG8_BAR; }
;     __device__ __forceinline__ bool operator()(pg8::f32x4 (&acc)[2][2][4][2], const pg8::Unit& u, int wr, int wc, int fr, int fq) const {
;     ...
;         for (int q = 0; q < 4; ++q) { const int ai = q >> 1, mh = q & 1, cb_ = q & 1;
;             if (q + 1 < 4) LOADX(cb_ ^ 1, q + 1);
;             __builtin_amdgcn_sched_barrier(0);
; #pragma unroll
;             for (int m = 0; m < 2; ++m)
; #pragma unroll
;                 for (int bj = 0; bj < 2; ++bj)
; #pragma unroll
;                     for (int n = 0; n < 2; ++n) { const pg8::f32x4 a = acc[ai][bj][2 * mh + m][n]; const f32x4 x = xv[cb_][m][bj][n];
;                         *(GAS f32x4*)(out + (size_t)(row0 + ai * 128 + (2 * mh + m) * 16) * DM + col0 + bj * 128 + n * 16) = (f32x4){x.x + a.x, x.y + a.y, x.z + a.z, x.w + a.w}; }
;             __builtin_amdgcn_sched_barrier(0);
;         }
	global_store_dwordx4 v[238:239], v[230:233], off offset:512
	global_store_dwordx4 v[240:241], v[234:237], off offset:512
	v_lshl_add_u64 v[154:155], v[216:217], 0, s[18:19]
	v_lshl_add_u64 v[156:157], v[216:217], 0, s[20:21]
	v_lshl_add_u64 v[78:79], v[214:215], 0, v[154:155]
	v_lshl_add_u64 v[98:99], v[214:215], 0, v[156:157]
	global_load_dwordx4 v[66:69], v[78:79], off
	global_load_dwordx4 v[70:73], v[78:79], off offset:64
	global_load_dwordx4 v[74:77], v[78:79], off offset:512
	s_nop 0
	global_load_dwordx4 v[78:81], v[78:79], off offset:576
	s_nop 0
	global_load_dwordx4 v[82:85], v[98:99], off
	global_load_dwordx4 v[86:89], v[98:99], off offset:64
	global_load_dwordx4 v[90:93], v[98:99], off offset:512
	s_nop 0
	global_load_dwordx4 v[98:101], v[98:99], off offset:576
	s_waitcnt vmcnt(23)
	v_pk_add_f32 v[62:63], v[62:63], v[94:95]
	v_lshl_add_u64 v[94:95], s[72:73], 0, v[150:151]
	v_lshl_add_u64 v[94:95], v[94:95], 0, v[142:143]
	s_waitcnt vmcnt(21)
	v_pk_add_f32 v[52:53], v[52:53], v[108:109]
	v_pk_add_f32 v[50:51], v[50:51], v[106:107]
	ds_write_b128 v224, v[50:53]
	s_waitcnt vmcnt(20)
	v_pk_add_f32 v[44:45], v[44:45], v[112:113]
	v_pk_add_f32 v[42:43], v[42:43], v[110:111]
	v_lshl_add_u64 v[50:51], s[72:73], 0, v[152:153]
	ds_write_b128 v225, v[42:45]
	ds_read_b128 v[230:233], v226
	ds_read_b128 v[234:237], v226 offset:8192
	v_lshl_add_u64 v[238:239], v[94:95], 0, v[242:243]
	v_lshl_add_u64 v[240:241], v[238:239], 0, s[100:101]
	s_waitcnt lgkmcnt(0)
	global_store_dwordx4 v[238:239], v[230:233], off offset:512
	global_store_dwordx4 v[240:241], v[234:237], off offset:512
	v_lshl_add_u64 v[50:51], v[50:51], 0, v[142:143]
	v_pk_add_f32 v[64:65], v[64:65], v[96:97]
	s_waitcnt vmcnt(21)
	v_pk_add_f32 v[44:45], v[56:57], v[116:117]
	v_pk_add_f32 v[42:43], v[54:55], v[114:115]
	v_pk_add_f32 v[60:61], v[60:61], v[104:105]
	v_pk_add_f32 v[58:59], v[58:59], v[102:103]
	ds_write_b128 v224, v[42:45]
	s_waitcnt vmcnt(19)
	v_pk_add_f32 v[36:37], v[36:37], v[124:125]
	v_pk_add_f32 v[34:35], v[34:35], v[122:123]
	v_pk_add_f32 v[44:45], v[48:49], v[120:121]
	v_pk_add_f32 v[42:43], v[46:47], v[118:119]
	s_waitcnt vmcnt(18)
	v_pk_add_f32 v[32:33], v[32:33], v[128:129]
	v_pk_add_f32 v[30:31], v[30:31], v[126:127]
	ds_write_b128 v227, v[62:65]
	ds_write_b128 v227, v[58:61] offset:64
	ds_read_b128 v[230:233], v228
	ds_read_b128 v[234:237], v228 offset:1152
	v_lshl_add_u64 v[238:239], v[94:95], 0, v[242:243]
	v_lshl_add_u64 v[240:241], v[238:239], 0, s[100:101]
	s_waitcnt lgkmcnt(0)
	global_store_dwordx4 v[238:239], v[230:233], off
	global_store_dwordx4 v[240:241], v[234:237], off
	ds_write_b128 v225, v[42:45]
	ds_read_b128 v[230:233], v226
	ds_read_b128 v[234:237], v226 offset:8192
	v_lshl_add_u64 v[238:239], v[50:51], 0, v[242:243]
	v_lshl_add_u64 v[240:241], v[238:239], 0, s[100:101]
	s_waitcnt lgkmcnt(0)
	global_store_dwordx4 v[238:239], v[230:233], off
	global_store_dwordx4 v[240:241], v[234:237], off
	ds_write_b128 v224, v[34:37]
	ds_write_b128 v225, v[30:33]
	ds_read_b128 v[230:233], v226
	ds_read_b128 v[234:237], v226 offset:8192
	v_lshl_add_u64 v[238:239], v[50:51], 0, v[242:243]
	v_lshl_add_u64 v[240:241], v[238:239], 0, s[100:101]
	s_waitcnt lgkmcnt(0)
	global_store_dwordx4 v[238:239], v[230:233], off offset:512
	global_store_dwordx4 v[240:241], v[234:237], off offset:512
	s_nop 0
	v_lshl_add_u64 v[34:35], s[72:73], 0, v[154:155]
	v_lshl_add_u64 v[34:35], v[34:35], 0, v[142:143]
	s_waitcnt vmcnt(13)
	v_pk_add_f32 v[20:21], v[20:21], v[76:77]
	v_pk_add_f32 v[18:19], v[18:19], v[74:75]
	ds_write_b128 v224, v[18:21]
	s_waitcnt vmcnt(12)
	v_pk_add_f32 v[12:13], v[12:13], v[80:81]
	v_pk_add_f32 v[10:11], v[10:11], v[78:79]
	v_lshl_add_u64 v[18:19], s[72:73], 0, v[156:157]
	ds_write_b128 v225, v[10:13]
	ds_read_b128 v[230:233], v226
	ds_read_b128 v[234:237], v226 offset:8192
	v_lshl_add_u64 v[238:239], v[34:35], 0, v[242:243]
	v_lshl_add_u64 v[240:241], v[238:239], 0, s[100:101]
	s_waitcnt lgkmcnt(0)
	global_store_dwordx4 v[238:239], v[230:233], off offset:512
	global_store_dwordx4 v[240:241], v[234:237], off offset:512
	v_lshl_add_u64 v[18:19], v[18:19], 0, v[142:143]
	v_pk_add_f32 v[32:33], v[40:41], v[68:69]
	s_waitcnt vmcnt(13)
	v_pk_add_f32 v[12:13], v[24:25], v[84:85]
	v_pk_add_f32 v[10:11], v[22:23], v[82:83]
	v_pk_add_f32 v[30:31], v[38:39], v[66:67]
	v_pk_add_f32 v[28:29], v[28:29], v[72:73]
	v_pk_add_f32 v[26:27], v[26:27], v[70:71]
	ds_write_b128 v224, v[10:13]
	s_waitcnt vmcnt(11)
	v_pk_add_f32 v[8:9], v[8:9], v[92:93]
	v_pk_add_f32 v[6:7], v[6:7], v[90:91]
	v_pk_add_f32 v[12:13], v[16:17], v[88:89]
	v_pk_add_f32 v[10:11], v[14:15], v[86:87]
	s_waitcnt vmcnt(10)
	v_pk_add_f32 v[4:5], v[4:5], v[100:101]
	v_pk_add_f32 v[2:3], v[2:3], v[98:99]
	ds_write_b128 v227, v[30:33]
	ds_write_b128 v227, v[26:29] offset:64
	ds_read_b128 v[230:233], v228
	ds_read_b128 v[234:237], v228 offset:1152
	v_lshl_add_u64 v[238:239], v[34:35], 0, v[242:243]
	v_lshl_add_u64 v[240:241], v[238:239], 0, s[100:101]
	s_waitcnt lgkmcnt(0)
	global_store_dwordx4 v[238:239], v[230:233], off
	global_store_dwordx4 v[240:241], v[234:237], off
	ds_write_b128 v225, v[10:13]
	ds_read_b128 v[230:233], v226
	ds_read_b128 v[234:237], v226 offset:8192
	v_lshl_add_u64 v[238:239], v[18:19], 0, v[242:243]
	v_lshl_add_u64 v[240:241], v[238:239], 0, s[100:101]
	s_waitcnt lgkmcnt(0)
	global_store_dwordx4 v[238:239], v[230:233], off
	global_store_dwordx4 v[240:241], v[234:237], off
	ds_write_b128 v224, v[6:9]
	ds_write_b128 v225, v[2:5]
	ds_read_b128 v[230:233], v226
	ds_read_b128 v[234:237], v226 offset:8192
	v_lshl_add_u64 v[238:239], v[18:19], 0, v[242:243]
	v_lshl_add_u64 v[240:241], v[238:239], 0, s[100:101]
	s_waitcnt lgkmcnt(0)
	global_store_dwordx4 v[238:239], v[230:233], off offset:512
	global_store_dwordx4 v[240:241], v[234:237], off offset:512
	s_and_b64 vcc, exec, s[0:1]
	s_mov_b32 s50, s22
	s_mov_b32 s30, s24
	s_mov_b64 s[36:37], s[28:29]
	s_mov_b64 s[34:35], s[26:27]
	s_cbranch_vccz .LBB0_715
	s_waitcnt vmcnt(0)
	s_cmpk_gt_u32 s2, 0xff
	s_cbranch_scc1 .LBB0_726
	s_barrier
